# combined: TW/AD beside products + no stage-L barrier, packed tanh, pass-1 row addresses from hoisted bases, batched P4 epilogue residual loads
# speedup vs baseline: 1.0154x; 1.0086x over previous
.LBB0_293:
	s_or_b64 exec, exec, s[4:5]
	v_and_b32_e32 v26, 64, v0
	s_and_b64 s[0:1], s[0:1], exec
	v_cmp_eq_u32_e32 vcc, 0, v26
	v_mov_b32_e32 v26, s69
	v_mov_b32_e32 v27, s67
	v_cndmask_b32_e32 v27, v26, v27, vcc
	v_mov_b32_e32 v26, s68
	v_mov_b32_e32 v28, s66
	s_movk_i32 s0, 0x100
	v_cndmask_b32_e32 v26, v26, v28, vcc
	v_cmp_gt_u32_e64 s[2:3], s0, v0
	v_mov_b32_e32 v28, 0x880
	v_mov_b32_e32 v46, 0x800
	v_lshrrev_b32_e32 v170, 1, v0
	v_and_b32_e32 v1, 63, v0
	v_writelane_b32 v250, s2, 21
	s_cselect_b32 s72, 17, 15
	s_add_u32 s88, s96, 0x2000000
	v_cndmask_b32_e64 v28, v28, v46, s[2:3]
	v_and_b32_e32 v46, 64, v170
	v_or3_b32 v28, v28, v46, v1
	v_lshlrev_b32_e32 v28, 2, v28
	v_lshl_add_u64 v[26:27], v[26:27], 0, v[28:29]
	global_load_dword v26, v[26:27], off
	s_addc_u32 s89, s97, 0
	s_add_i32 s0, 0, 0x24000
	s_lshl_b32 s55, s50, 4
	s_cmpk_gt_u32 s51, 0xff
	s_cselect_b64 s[4:5], -1, 0
	s_cmpk_lt_u32 s51, 0x100
	s_cselect_b64 vcc, -1, 0
	v_writelane_b32 v250, s3, 22
	s_and_b64 s[2:3], vcc, exec
	s_cselect_b32 s3, s45, s47
	s_cselect_b32 s2, s44, s46
	v_and_b32_e32 v110, 48, v0
	v_mov_b32_e32 v111, v29
	v_lshl_add_u32 v27, v0, 2, s0
	v_lshl_add_u64 v[112:113], s[2:3], 0, v[110:111]
	s_movk_i32 s2, 0x340
	v_cmp_gt_u32_e64 s[2:3], s2, v0
	v_bfe_u32 v171, v0, 4, 2
	s_mov_b32 s23, 0x1dc00
	v_writelane_b32 v250, s2, 23
	v_and_b32_e32 v166, 15, v0
	v_lshlrev_b32_e32 v173, 2, v171
	v_writelane_b32 v250, s3, 24
	s_mov_b32 s3, 0xd000
	s_cselect_b32 s2, 0, 0x4000
	s_cselect_b32 s22, s3, 0xf800
	v_or_b32_e32 v54, 16, v166
	v_or_b32_e32 v51, 32, v166
	v_bitop3_b32 v28, s50, v171, 3 bitop3:0x6c
	s_movk_i32 s73, 0xa0
	v_or_b32_e32 v49, 48, v1
	v_lshlrev_b32_e32 v48, 6, v28
	v_lshlrev_b32_e32 v28, 2, v166
	v_mul_u32_u24_e32 v46, 0xa0, v49
	v_lshlrev_b32_e32 v188, 2, v1
	v_and_b32_e32 v72, 4, v173
	v_lshrrev_b32_e32 v111, 3, v0
	v_or_b32_e32 v184, s55, v166
	v_mul_lo_u32 v185, v184, s73
	v_lshlrev_b32_e32 v172, 3, v171
	v_lshlrev_b32_e32 v61, 1, v166
	v_lshl_add_u32 v63, v166, 6, 0
	s_mov_b32 s1, 0
	v_and_or_b32 v176, s55, 48, v166
	v_or_b32_e32 v177, 0x200, v0
	v_or_b32_e32 v178, 0x400, v0
	v_or_b32_e32 v179, 0x600, v0
	v_mul_u32_u24_e32 v167, 0xa0, v166
	v_add_u32_e32 v205, 0x24800, v175
	v_lshrrev_b32_e32 v187, 6, v0
	v_add_u32_e32 v215, v63, v110
	v_mov_b32_e32 v220, 0x90
	v_mov_b32_e32 v138, 0
	s_waitcnt vmcnt(0)
	ds_write_b32 v27, v26
	v_and_b32_e32 v27, 7, v0
	v_lshl_add_u32 v180, v27, 5, s0
	s_mov_b32 s0, 0x8000
	s_cselect_b32 s0, s0, 0xa800
	s_add_i32 s0, s0, 0
	v_add_u32_e32 v181, s0, v110
	s_add_i32 s0, s2, 0
	v_lshl_add_u32 v47, v171, 10, s0
	s_lshl_b32 s0, s50, 8
	s_lshl_b32 s92, s50, 1
	s_add_i32 s0, s0, 0
	s_cmp_lt_u32 s51, 64
	s_cselect_b64 s[8:9], -1, 0
	s_cmpk_gt_u32 s51, 0x7f
	s_cselect_b64 s[10:11], -1, 0
	s_cmpk_gt_u32 s51, 0xbf
	s_cselect_b64 s[12:13], -1, 0
	s_cmpk_gt_u32 s51, 0x13f
	s_cselect_b64 s[14:15], -1, 0
	s_cmpk_gt_u32 s51, 0x17f
	s_cselect_b64 s[16:17], -1, 0
	s_cmpk_gt_u32 s51, 0x1bf
	s_cselect_b64 s[18:19], -1, 0
	s_cmpk_gt_u32 s51, 0x1ff
	v_writelane_b32 v250, s0, 25
	s_cselect_b64 s[20:21], -1, 0
	s_lshr_b32 s0, s51, 7
	s_cmp_eq_u32 s0, 2
	s_cselect_b64 s[2:3], -1, 0
	s_and_b64 s[6:7], s[2:3], exec
	s_cselect_b32 s6, s23, 0x20400
	s_cmp_lg_u32 s0, 1
	s_cselect_b32 s23, s6, 0x4000
	s_cmpk_lt_u32 s51, 0x80
	s_cselect_b64 s[24:25], -1, 0
	s_and_b64 s[6:7], s[24:25], exec
	s_cselect_b32 s6, 0, s23
	v_writelane_b32 v250, s24, 26
	s_or_b64 s[2:3], s[24:25], s[2:3]
	s_mov_b32 s7, 0x14800
	s_and_b64 s[2:3], s[2:3], exec
	s_cselect_b32 s7, s7, 0x12000
	s_bfe_u32 s54, s51, 0x10006
	s_bitcmp1_b32 s51, 6
	s_cselect_b64 s[2:3], -1, 0
	s_add_i32 s22, s22, 0
	v_writelane_b32 v250, s25, 27
	v_mov_b32_e32 v53, s22
	v_cmp_lt_u32_e64 s[22:23], v173, v166
	v_cmp_le_u32_e64 s[24:25], v173, v166
	s_add_i32 s7, s7, 0
	v_cndmask_b32_e64 v56, 0, 1, s[22:23]
	v_cndmask_b32_e64 v57, 0, 1, s[24:25]
	v_cndmask_b32_e32 v56, v57, v56, vcc
	v_and_b32_e32 v56, 1, v56
	v_cmp_eq_u32_e64 s[22:23], 1, v56
	v_or_b32_e32 v56, 17, v173
	v_cmp_lt_u32_e64 s[24:25], v56, v54
	v_cmp_le_u32_e64 s[26:27], v56, v54
	s_add_i32 s6, s6, 0
	v_cndmask_b32_e64 v56, 0, 1, s[24:25]
	v_cndmask_b32_e64 v57, 0, 1, s[26:27]
	v_cndmask_b32_e32 v56, v57, v56, vcc
	v_and_b32_e32 v56, 1, v56
	v_mov_b32_e32 v52, s7
	v_mov_b32_e32 v55, s6
	v_cmp_eq_u32_e64 s[6:7], 1, v56
	v_or_b32_e32 v56, 18, v173
	v_cmp_lt_u32_e64 s[26:27], v56, v54
	v_cmp_le_u32_e64 s[28:29], v56, v54
	v_writelane_b32 v250, s6, 28
	v_cndmask_b32_e64 v56, 0, 1, s[26:27]
	v_cndmask_b32_e64 v57, 0, 1, s[28:29]
	v_cndmask_b32_e32 v56, v57, v56, vcc
	v_and_b32_e32 v56, 1, v56
	v_writelane_b32 v250, s7, 29
	v_cmp_eq_u32_e64 s[6:7], 1, v56
	v_or_b32_e32 v56, 19, v173
	v_cmp_lt_u32_e64 s[28:29], v56, v54
	v_cmp_le_u32_e64 s[30:31], v56, v54
	v_writelane_b32 v250, s6, 30
	v_cndmask_b32_e64 v54, 0, 1, s[28:29]
	v_cndmask_b32_e64 v56, 0, 1, s[30:31]
	v_cndmask_b32_e32 v54, v56, v54, vcc
	v_and_b32_e32 v54, 1, v54
	v_writelane_b32 v250, s7, 31
	v_cmp_eq_u32_e64 s[6:7], 1, v54
	v_or_b32_e32 v54, 33, v173
	v_cmp_lt_u32_e64 s[30:31], v54, v51
	v_cmp_le_u32_e64 s[34:35], v54, v51
	v_writelane_b32 v250, s6, 32
	v_cndmask_b32_e64 v54, 0, 1, s[30:31]
	v_cndmask_b32_e64 v57, 0, 1, s[34:35]
	v_cndmask_b32_e32 v54, v57, v54, vcc
	v_and_b32_e32 v54, 1, v54
	v_writelane_b32 v250, s7, 33
	v_cmp_eq_u32_e64 s[6:7], 1, v54
	v_or_b32_e32 v54, 34, v173
	v_cmp_lt_u32_e64 s[34:35], v54, v51
	v_cmp_le_u32_e64 s[36:37], v54, v51
	v_writelane_b32 v250, s6, 34
	v_cndmask_b32_e64 v54, 0, 1, s[34:35]
	v_cndmask_b32_e64 v57, 0, 1, s[36:37]
	v_cndmask_b32_e32 v54, v57, v54, vcc
	v_and_b32_e32 v54, 1, v54
	v_writelane_b32 v250, s7, 35
	v_cmp_eq_u32_e64 s[6:7], 1, v54
	v_or_b32_e32 v54, 35, v173
	v_cmp_lt_u32_e64 s[36:37], v54, v51
	v_cmp_le_u32_e64 s[38:39], v54, v51
	v_writelane_b32 v250, s6, 36
	v_cndmask_b32_e64 v51, 0, 1, s[36:37]
	v_cndmask_b32_e64 v54, 0, 1, s[38:39]
	v_cndmask_b32_e32 v51, v54, v51, vcc
	v_and_b32_e32 v51, 1, v51
	v_add3_u32 v182, v47, v48, v28
	v_mad_u32_u24 v47, v166, s73, v52
	v_mad_u32_u24 v48, v166, s73, v53
	v_writelane_b32 v250, s7, 37
	v_cmp_eq_u32_e64 s[6:7], 1, v51
	v_mad_u32_u24 v51, v49, s73, v53
	v_mad_u32_u24 v53, v49, s73, v52
	v_cndmask_b32_e64 v52, 0, 1, vcc
	v_writelane_b32 v250, s6, 38
	v_or_b32_e32 v52, v173, v52
	v_mad_u32_u24 v183, v166, s73, v55
	v_writelane_b32 v250, s7, 39
	v_cmp_gt_u32_e64 s[6:7], v166, v52
	v_or_b32_e32 v52, 2, v173
	v_cmp_lt_u32_e64 s[40:41], v52, v166
	v_cmp_le_u32_e64 s[42:43], v52, v166
	v_writelane_b32 v250, s6, 40
	v_cndmask_b32_e64 v52, 0, 1, s[40:41]
	v_cndmask_b32_e64 v54, 0, 1, s[42:43]
	v_cndmask_b32_e32 v52, v54, v52, vcc
	v_and_b32_e32 v52, 1, v52
	v_writelane_b32 v250, s7, 41
	v_cmp_eq_u32_e64 s[6:7], 1, v52
	v_or_b32_e32 v52, 3, v173
	v_cmp_lt_u32_e64 s[42:43], v52, v166
	v_cmp_le_u32_e64 s[44:45], v52, v166
	v_writelane_b32 v250, s6, 42
	v_cndmask_b32_e64 v52, 0, 1, s[42:43]
	v_cndmask_b32_e64 v54, 0, 1, s[44:45]
	v_cndmask_b32_e32 v52, v54, v52, vcc
	v_and_b32_e32 v52, 1, v52
	v_writelane_b32 v250, s7, 43
	v_cmp_eq_u32_e64 s[6:7], 1, v52
	v_or_b32_e32 v52, 48, v173
	v_cmp_lt_u32_e64 s[44:45], v52, v49
	v_cmp_le_u32_e64 s[46:47], v52, v49
	v_mad_u32_u24 v189, v49, s73, v55
	v_cndmask_b32_e64 v54, 0, 1, s[44:45]
	v_cndmask_b32_e64 v55, 0, 1, s[46:47]
	v_cndmask_b32_e32 v54, v55, v54, vcc
	v_writelane_b32 v250, s6, 44
	v_and_b32_e32 v54, 1, v54
	s_mov_b32 s25, s50
	v_writelane_b32 v250, s7, 45
	v_cmp_eq_u32_e64 s[6:7], 1, v54
	v_or_b32_e32 v54, 49, v173
	v_cmp_lt_u32_e64 s[46:47], v54, v49
	v_cmp_le_u32_e64 s[48:49], v54, v49
	v_writelane_b32 v250, s6, 46
	v_cndmask_b32_e64 v54, 0, 1, s[46:47]
	v_cndmask_b32_e64 v55, 0, 1, s[48:49]
	v_cndmask_b32_e32 v54, v55, v54, vcc
	v_and_b32_e32 v54, 1, v54
	v_writelane_b32 v250, s7, 47
	v_cmp_eq_u32_e64 s[6:7], 1, v54
	v_or_b32_e32 v54, 50, v173
	v_cmp_lt_u32_e64 s[48:49], v54, v49
	s_mov_b32 s24, s51
	v_cmp_le_u32_e64 s[50:51], v54, v49
	v_cndmask_b32_e64 v54, 0, 1, s[48:49]
	v_writelane_b32 v250, s6, 48
	v_cndmask_b32_e64 v55, 0, 1, s[50:51]
	v_cndmask_b32_e32 v54, v55, v54, vcc
	v_and_b32_e32 v54, 1, v54
	v_writelane_b32 v250, s7, 49
	v_cmp_eq_u32_e64 s[6:7], 1, v54
	v_or_b32_e32 v54, 51, v173
	v_cmp_lt_u32_e64 s[50:51], v54, v49
	v_cmp_le_u32_e64 s[52:53], v54, v49
	v_writelane_b32 v250, s6, 50
	v_cndmask_b32_e64 v49, 0, 1, s[50:51]
	v_cndmask_b32_e64 v54, 0, 1, s[52:53]
	v_cndmask_b32_e32 v49, v54, v49, vcc
	v_and_b32_e32 v49, 1, v49
	v_writelane_b32 v250, s7, 51
	v_cmp_eq_u32_e64 s[6:7], 1, v49
	v_lshlrev_b32_e32 v49, 1, v52
	v_add_u32_e32 v57, 0, v28
	v_writelane_b32 v250, s6, 52
	v_lshl_or_b32 v52, s54, 5, v166
	v_mul_u32_u24_e32 v58, 0x90, v52
	v_writelane_b32 v250, s7, 53
	s_movk_i32 s7, 0x9c
	v_or_b32_e32 v52, 16, v52
	v_mad_u32_u24 v60, v166, s7, v57
	s_movk_i32 s7, 0x480
	v_mul_u32_u24_e32 v59, 0x90, v52
	v_mad_u32_u24 v52, v171, s7, 0
	s_and_b32 s7, s24, 0xffffffc0
	s_lshl_b32 s26, s0, 4
	v_add3_u32 v191, v52, s7, v28
	v_lshlrev_b32_e32 v28, 9, v171
	v_or_b32_e32 v168, s26, v166
	s_movk_i32 s6, 0x90
	v_writelane_b32 v250, s24, 54
	v_sub_u32_e32 v28, v52, v28
	v_lshl_add_u32 v62, s25, 5, v28
	v_writelane_b32 v250, s55, 55
	v_mul_lo_u32 v28, v168, s6
	s_add_i32 s6, 0, 0x20400
	s_add_i32 s93, 0, 0x1b800
	s_add_i32 s40, 0, 0x12000
	s_and_b32 s7, s92, 2
	s_add_i32 s24, 0, 0x1dc00
	v_add_u32_e32 v193, s6, v110
	s_add_i32 s6, s26, 64
	s_add_i32 s41, 0, 0x19400
	s_add_i32 s42, 0, 0x17000
	v_writelane_b32 v250, s25, 56
	s_bitcmp1_b32 s25, 0
	v_writelane_b32 v250, s26, 57
	v_or_b32_e32 v73, s26, v173
	s_movk_i32 s43, 0x120
	v_add_u32_e32 v66, s93, v28
	v_or_b32_e32 v52, s6, v166
	v_add_u32_e32 v68, s42, v28
	v_add_u32_e32 v69, s41, v28
	v_lshl_or_b32 v70, s7, 4, v166
	s_cselect_b64 s[62:63], -1, 0
	s_lshl_b32 s6, s7, 10
	v_lshl_or_b32 v169, s0, 8, v188
	s_or_b32 s0, s7, 1
	v_mul_lo_u32 v28, v73, s43
	v_writelane_b32 v250, s54, 58
	s_lshl_b32 s7, s54, 7
	v_add_u32_e32 v192, s24, v110
	s_add_i32 s24, 0, 0x22c00
	v_lshl_or_b32 v71, s0, 4, v166
	s_lshl_b32 s0, s0, 10
	v_add3_u32 v202, v57, v28, s7
	v_lshlrev_b32_e32 v28, 1, v73
	s_mov_b32 s7, 0x1ffffff0
	v_readlane_b32 s26, v250, 19
	v_and_or_b32 v57, v28, s7, v166
	v_readlane_b32 s27, v250, 20
	s_add_u32 s38, s66, 0x1000
	v_add_u32_e32 v203, 0, v28
	v_lshl_add_u64 v[118:119], s[26:27], 0, v[28:29]
	v_lshlrev_b32_e32 v28, 3, v57
	s_addc_u32 s39, s67, 0
	v_add_u32_e32 v114, s6, v169
	v_add_u32_e32 v57, s6, v28
	s_add_u32 s6, s68, 0x800
	s_addc_u32 s7, s69, 0
	v_or_b32_e32 v120, v57, v72
	v_or_b32_e32 v57, 1, v73
	v_cmp_eq_u32_e64 s[52:53], v73, v70
	v_add_u32_e32 v28, s0, v28
	v_writelane_b32 v250, s6, 59
	v_cmp_eq_u32_e32 vcc, v57, v70
	v_cndmask_b32_e64 v122, 0, 1.0, s[52:53]
	v_or_b32_e32 v124, v28, v72
	v_cmp_eq_u32_e64 s[52:53], v73, v71
	v_or_b32_e32 v28, 3, v73
	v_writelane_b32 v250, s7, 60
	s_add_u32 s6, s66, 0x800
	v_cndmask_b32_e64 v123, 0, 1.0, vcc
	v_cmp_eq_u32_e32 vcc, v57, v71
	v_cndmask_b32_e64 v126, 0, 1.0, s[52:53]
	v_or_b32_e32 v57, 2, v73
	v_cmp_eq_u32_e64 s[52:53], v28, v70
	s_addc_u32 s7, s67, 0
	v_mad_u32_u24 v26, v111, s73, 0
	v_lshlrev_b32_e32 v27, 4, v27
	v_mul_lo_u32 v186, v168, s73
	v_mul_lo_u32 v52, v52, s73
	v_cndmask_b32_e64 v127, 0, 1.0, vcc
	v_cmp_eq_u32_e32 vcc, v57, v70
	v_cndmask_b32_e64 v129, 0, 1.0, s[52:53]
	v_cmp_eq_u32_e64 s[52:53], v28, v71
	v_writelane_b32 v250, s6, 61
	v_lshlrev_b32_e32 v28, 5, v0
	v_add_u32_e32 v50, 0xa00, v183
	v_add_u32_e32 v56, 0x1400, v183
	v_add_u32_e32 v55, 0, v186
	v_add_u32_e32 v190, s93, v110
	v_add_u32_e32 v64, s40, v185
	v_add_u32_e32 v65, s40, v186
	v_add_u32_e32 v67, s40, v52
	v_lshlrev_b32_e32 v52, 6, v70
	v_lshlrev_b32_e32 v54, 6, v71
	v_add_u32_e32 v116, s0, v169
	v_cndmask_b32_e64 v128, 0, 1.0, vcc
	v_cmp_eq_u32_e32 vcc, v57, v71
	v_writelane_b32 v250, s7, 62
	s_add_u32 s6, s68, 0x1000
	v_and_b32_e32 v28, 0x3800, v28
	v_add_u32_e32 v206, v26, v27
	v_add_u32_e32 v207, v181, v46
	v_mbcnt_lo_u32_b32 v26, -1, 0
	v_mov_b32_e32 v46, 0
	v_add_u32_e32 v194, s41, v110
	v_add_u32_e32 v195, s40, v110
	v_mul_u32_u24_e32 v196, 0xa0, v70
	v_mul_u32_u24_e32 v197, 0x90, v70
	v_lshl_add_u32 v198, v70, 2, s24
	v_ashrrev_i32_e32 v115, 31, v114
	v_mul_u32_u24_e32 v199, 0xa0, v71
	v_mul_u32_u24_e32 v200, 0x90, v71
	v_lshl_add_u32 v201, v71, 2, s24
	v_ashrrev_i32_e32 v117, 31, v116
	v_lshl_add_u32 v204, v73, 2, s24
	v_ashrrev_i32_e32 v121, 31, v120
	v_ashrrev_i32_e32 v125, 31, v124
	v_cndmask_b32_e64 v131, 0, 1.0, s[52:53]
	v_cndmask_b32_e64 v130, 0, 1.0, vcc
	s_addc_u32 s7, s69, 0
	v_lshl_add_u64 v[132:133], s[70:71], 0, v[28:29]
	s_mov_b32 s34, -1
	s_movk_i32 s71, 0x630
	s_mov_b32 s44, 0x3e0f83e1
	s_movk_i32 s45, 0xfdf0
	s_movk_i32 s46, 0x2940
	s_mov_b32 s47, 0x5040100
	s_mov_b32 s70, 0xbf60033a
	v_mbcnt_hi_u32_b32 v208, -1, v26
	s_add_i32 s48, 0, 0x12280
	s_movk_i32 s49, 0x2600
	v_add_u32_e32 v209, v50, v172
	v_add_u32_e32 v210, v51, v110
	v_add_u32_e32 v211, v53, v110
	v_add_u32_e32 v212, v189, v49
	v_add_u32_e32 v213, v60, v172
	v_add_u32_e32 v214, v62, v61
	v_add_u32_e32 v216, v64, v172
	v_add_u32_e32 v217, v65, v110
	v_lshlrev_b32_e32 v134, 1, v52
	v_add_u32_e32 v218, v68, v110
	v_add_u32_e32 v219, v69, v110
	v_lshlrev_b32_e32 v136, 1, v54
	v_add_u32_e32 v221, v47, v110
	v_add_u32_e32 v222, v48, v110
	v_add_u32_e32 v223, v56, v172
	v_mov_b32_e32 v139, v46
	v_add_u32_e32 v224, v55, v110
	v_add_u32_e32 v225, v190, v58
	v_add_u32_e32 v226, v190, v59
	v_add_u32_e32 v227, v66, v110
	v_add_u32_e32 v228, v67, v110
	s_mov_b32 s51, 0
	v_lshrrev_b32_e32 v26, 3, v0
	v_and_b32_e32 v27, 7, v0
	v_mul_u32_u24_e32 v26, 0x2600, v26
	v_lshl_add_u32 v251, v27, 4, v26
	v_mov_b32_e32 v26, v0
	v_lshrrev_b32_e32 v27, 4, v26
	v_mul_u32_u24_e32 v27, 0x7c2, v27
	v_lshrrev_b32_e32 v27, 16, v27
	v_mul_u32_u24_e32 v28, 0x210, v27
	v_sub_u32_e32 v26, v26, v28
	v_lshrrev_b32_e32 v28, 3, v26
	v_and_b32_e32 v26, 7, v26
	v_mul_u32_u24_e32 v28, 0x2600, v28
	v_lshl_add_u32 v28, v27, 10, v28
	v_lshl_add_u32 v252, v26, 4, v28
	v_add_u32_e32 v26, 0x200, v0
	v_lshrrev_b32_e32 v27, 4, v26
	v_mul_u32_u24_e32 v27, 0x7c2, v27
	v_lshrrev_b32_e32 v27, 16, v27
	v_mul_u32_u24_e32 v28, 0x210, v27
	v_sub_u32_e32 v26, v26, v28
	v_lshrrev_b32_e32 v28, 3, v26
	v_and_b32_e32 v26, 7, v26
	v_mul_u32_u24_e32 v28, 0x2600, v28
	v_lshl_add_u32 v28, v27, 10, v28
	v_lshl_add_u32 v253, v26, 4, v28
	v_add_u32_e32 v26, 0x400, v0
	v_lshrrev_b32_e32 v27, 4, v26
	v_mul_u32_u24_e32 v27, 0x7c2, v27
	v_lshrrev_b32_e32 v27, 16, v27
	v_mul_u32_u24_e32 v28, 0x210, v27
	v_sub_u32_e32 v26, v26, v28
	v_lshrrev_b32_e32 v28, 3, v26
	v_and_b32_e32 v26, 7, v26
	v_mul_u32_u24_e32 v28, 0x2600, v28
	v_lshl_add_u32 v28, v27, 10, v28
	v_lshl_add_u32 v254, v26, 4, v28
	v_add_u32_e32 v26, 0x600, v0
	v_lshrrev_b32_e32 v27, 4, v26
	v_mul_u32_u24_e32 v27, 0x7c2, v27
	v_lshrrev_b32_e32 v27, 16, v27
	v_mul_u32_u24_e32 v28, 0x210, v27
	v_sub_u32_e32 v26, v26, v28
	v_lshrrev_b32_e32 v28, 3, v26
	v_and_b32_e32 v26, 7, v26
	v_mul_u32_u24_e32 v28, 0x2600, v28
	v_lshl_add_u32 v28, v27, 10, v28
	v_lshl_add_u32 v255, v26, 4, v28
	v_mov_b32_e32 v26, v0
	v_cmp_lt_u32_e32 vcc, 0x20f, v26
	s_nop 1
	v_cndmask_b32_e64 v27, 0, 1, vcc
	v_cmp_lt_u32_e32 vcc, 0x41f, v26
	s_nop 1
	v_addc_co_u32_e32 v27, vcc, 0, v27, vcc
	v_mul_u32_u24_e32 v28, 0x210, v27
	v_sub_u32_e32 v28, v26, v28
	v_lshrrev_b32_e32 v28, 3, v28
	v_mul_u32_u24_e32 v28, 0xa0, v28
	v_mul_u32_u24_e32 v27, 0x2940, v27
	v_and_b32_e32 v26, 7, v26
	v_lshlrev_b32_e32 v26, 4, v26
	v_add3_u32 v110, v27, v28, v26
	v_add_u32_e32 v26, 0x200, v0
	v_cmp_lt_u32_e32 vcc, 0x20f, v26
	s_nop 1
	v_cndmask_b32_e64 v27, 0, 1, vcc
	v_cmp_lt_u32_e32 vcc, 0x41f, v26
	s_nop 1
	v_addc_co_u32_e32 v27, vcc, 0, v27, vcc
	v_mul_u32_u24_e32 v28, 0x210, v27
	v_sub_u32_e32 v28, v26, v28
	v_lshrrev_b32_e32 v28, 3, v28
	v_mul_u32_u24_e32 v28, 0xa0, v28
	v_mul_u32_u24_e32 v27, 0x2940, v27
	v_and_b32_e32 v26, 7, v26
	v_lshlrev_b32_e32 v26, 4, v26
	v_add3_u32 v111, v27, v28, v26
	v_add_u32_e32 v26, 0x400, v0
	v_cmp_lt_u32_e32 vcc, 0x20f, v26
	s_nop 1
	v_cndmask_b32_e64 v27, 0, 1, vcc
	v_cmp_lt_u32_e32 vcc, 0x41f, v26
	s_nop 1
	v_addc_co_u32_e32 v27, vcc, 0, v27, vcc
	v_mul_u32_u24_e32 v28, 0x210, v27
	v_sub_u32_e32 v28, v26, v28
	v_lshrrev_b32_e32 v28, 3, v28
	v_mul_u32_u24_e32 v28, 0xa0, v28
	v_mul_u32_u24_e32 v27, 0x2940, v27
	v_and_b32_e32 v26, 7, v26
	v_lshlrev_b32_e32 v26, 4, v26
	v_add3_u32 v166, v27, v28, v26
	v_add_u32_e32 v26, 0x600, v0
	v_cmp_lt_u32_e32 vcc, 0x20f, v26
	s_nop 1
	v_cndmask_b32_e64 v27, 0, 1, vcc
	v_cmp_lt_u32_e32 vcc, 0x41f, v26
	s_nop 1
	v_addc_co_u32_e32 v27, vcc, 0, v27, vcc
	v_mul_u32_u24_e32 v28, 0x210, v27
	v_sub_u32_e32 v28, v26, v28
	v_lshrrev_b32_e32 v28, 3, v28
	v_mul_u32_u24_e32 v28, 0xa0, v28
	v_mul_u32_u24_e32 v27, 0x2940, v27
	v_and_b32_e32 v26, 7, v26
	v_lshlrev_b32_e32 v26, 4, v26
	v_add3_u32 v168, v27, v28, v26
	v_lshrrev_b32_e32 v26, 5, v0
	v_and_b32_e32 v27, 31, v0
	v_mul_u32_u24_e32 v26, 0x280, v26
	v_lshlrev_b32_e32 v27, 2, v27
	v_add_u32_e32 v169, v26, v27
	v_add_u32_e32 v169, 0x28a0, v169
	v_sub_u32_e32 v170, v27, v26
	v_add_u32_e32 v170, 0x5140, v170
	s_branch .LBB0_295

.Ltw_do:
	s_cmp_lg_u32 s51, s72
	s_cbranch_scc0 .Ltw_skip
	s_add_i32 s37, s51, s33
	s_and_b32 s37, s37, 1
	v_lshl_add_u32 v47, s37, 9, v180
	ds_read_b128 v[66:69], v47
	ds_read_b128 v[70:73], v47 offset:16
	ds_read_b128 v[74:77], v47 offset:256
	ds_read_b128 v[78:81], v47 offset:272
	s_mov_b32 s30, 0x4038aa3b
	s_waitcnt lgkmcnt(1)
	v_lshlrev_b32_e32 v26, 16, v2
	v_and_b32_e32 v27, 0xffff0000, v2
	v_lshlrev_b32_e32 v48, 16, v10
	v_and_b32_e32 v49, 0xffff0000, v10
	v_lshlrev_b32_e32 v82, 16, v6
	v_and_b32_e32 v83, 0xffff0000, v6
	v_pk_add_f32 v[48:49], v[48:49], v[26:27] neg_lo:[0,1] neg_hi:[0,1]
	v_pk_add_f32 v[82:83], v[82:83], v[26:27] neg_lo:[0,1] neg_hi:[0,1]
	v_pk_fma_f32 v[48:49], v[48:49], v[66:67], v[26:27]
	v_pk_fma_f32 v[48:49], v[82:83], v[74:75], v[48:49]
	v_pk_mul_f32 v[66:67], v[48:49], s[30:31] op_sel_hi:[1,0]
	v_exp_f32_e32 v66, v66
	v_exp_f32_e32 v67, v67
	v_lshlrev_b32_e32 v26, 16, v3
	v_and_b32_e32 v27, 0xffff0000, v3
	v_lshlrev_b32_e32 v48, 16, v11
	v_and_b32_e32 v49, 0xffff0000, v11
	v_lshlrev_b32_e32 v82, 16, v7
	v_and_b32_e32 v83, 0xffff0000, v7
	v_pk_add_f32 v[48:49], v[48:49], v[26:27] neg_lo:[0,1] neg_hi:[0,1]
	v_pk_add_f32 v[82:83], v[82:83], v[26:27] neg_lo:[0,1] neg_hi:[0,1]
	v_pk_fma_f32 v[48:49], v[48:49], v[68:69], v[26:27]
	v_pk_fma_f32 v[48:49], v[82:83], v[76:77], v[48:49]
	v_pk_mul_f32 v[68:69], v[48:49], s[30:31] op_sel_hi:[1,0]
	v_pk_add_f32 v[66:67], v[66:67], 1.0 op_sel_hi:[1,0]
	v_rcp_f32_e32 v66, v66
	v_rcp_f32_e32 v67, v67
	v_exp_f32_e32 v68, v68
	v_exp_f32_e32 v69, v69
	s_waitcnt lgkmcnt(0)
	v_lshlrev_b32_e32 v26, 16, v4
	v_and_b32_e32 v27, 0xffff0000, v4
	v_lshlrev_b32_e32 v48, 16, v12
	v_and_b32_e32 v49, 0xffff0000, v12
	v_lshlrev_b32_e32 v82, 16, v8
	v_and_b32_e32 v83, 0xffff0000, v8
	v_pk_add_f32 v[48:49], v[48:49], v[26:27] neg_lo:[0,1] neg_hi:[0,1]
	v_pk_add_f32 v[82:83], v[82:83], v[26:27] neg_lo:[0,1] neg_hi:[0,1]
	v_pk_fma_f32 v[48:49], v[48:49], v[70:71], v[26:27]
	v_pk_fma_f32 v[48:49], v[82:83], v[78:79], v[48:49]
	v_pk_mul_f32 v[70:71], v[48:49], s[30:31] op_sel_hi:[1,0]
	v_pk_add_f32 v[68:69], v[68:69], 1.0 op_sel_hi:[1,0]
	v_rcp_f32_e32 v68, v68
	v_rcp_f32_e32 v69, v69
	v_exp_f32_e32 v70, v70
	v_exp_f32_e32 v71, v71
	v_lshlrev_b32_e32 v26, 16, v5
	v_and_b32_e32 v27, 0xffff0000, v5
	v_lshlrev_b32_e32 v48, 16, v13
	v_and_b32_e32 v49, 0xffff0000, v13
	v_lshlrev_b32_e32 v82, 16, v9
	v_and_b32_e32 v83, 0xffff0000, v9
	v_pk_add_f32 v[48:49], v[48:49], v[26:27] neg_lo:[0,1] neg_hi:[0,1]
	v_pk_add_f32 v[82:83], v[82:83], v[26:27] neg_lo:[0,1] neg_hi:[0,1]
	v_pk_fma_f32 v[48:49], v[48:49], v[72:73], v[26:27]
	v_pk_fma_f32 v[48:49], v[82:83], v[80:81], v[48:49]
	v_pk_mul_f32 v[72:73], v[48:49], s[30:31] op_sel_hi:[1,0]
	v_pk_add_f32 v[70:71], v[70:71], 1.0 op_sel_hi:[1,0]
	v_rcp_f32_e32 v70, v70
	v_rcp_f32_e32 v71, v71
	v_exp_f32_e32 v72, v72
	v_exp_f32_e32 v73, v73
	v_pk_fma_f32 v[66:67], v[66:67], 2.0, 1.0 op_sel_hi:[1,0,0] neg_lo:[1,0,0] neg_hi:[1,0,0]
	v_pk_fma_f32 v[68:69], v[68:69], 2.0, 1.0 op_sel_hi:[1,0,0] neg_lo:[1,0,0] neg_hi:[1,0,0]
	v_pk_add_f32 v[72:73], v[72:73], 1.0 op_sel_hi:[1,0]
	v_rcp_f32_e32 v72, v72
	v_rcp_f32_e32 v73, v73
	v_pk_fma_f32 v[70:71], v[70:71], 2.0, 1.0 op_sel_hi:[1,0,0] neg_lo:[1,0,0] neg_hi:[1,0,0]
	v_cvt_pk_bf16_f32 v74, v66, v67
	v_cvt_pk_bf16_f32 v75, v68, v69
	v_cvt_pk_bf16_f32 v76, v70, v71
	v_pk_fma_f32 v[72:73], v[72:73], 2.0, 1.0 op_sel_hi:[1,0,0] neg_lo:[1,0,0] neg_hi:[1,0,0]
	v_cvt_pk_bf16_f32 v77, v72, v73
	ds_write_b128 v206, v[74:77] offset:32768
	ds_read_b128 v[66:69], v47 offset:1024
	ds_read_b128 v[70:73], v47 offset:1040
	ds_read_b128 v[74:77], v47 offset:1280
	ds_read_b128 v[78:81], v47 offset:1296
	v_lshlrev_b32_e32 v26, 16, v14
	v_and_b32_e32 v27, 0xffff0000, v14
	v_lshlrev_b32_e32 v48, 16, v22
	v_and_b32_e32 v49, 0xffff0000, v22
	v_lshlrev_b32_e32 v82, 16, v18
	v_and_b32_e32 v83, 0xffff0000, v18
	v_pk_add_f32 v[48:49], v[48:49], v[26:27] neg_lo:[0,1] neg_hi:[0,1]
	s_waitcnt lgkmcnt(3)
	v_pk_fma_f32 v[48:49], v[48:49], v[66:67], v[26:27]
	v_pk_add_f32 v[26:27], v[82:83], v[26:27] neg_lo:[0,1] neg_hi:[0,1]
	v_lshlrev_b32_e32 v66, 16, v23
	s_waitcnt lgkmcnt(1)
	v_pk_fma_f32 v[26:27], v[26:27], v[74:75], v[48:49]
	v_lshlrev_b32_e32 v48, 16, v15
	v_and_b32_e32 v49, 0xffff0000, v15
	v_and_b32_e32 v67, 0xffff0000, v23
	v_lshlrev_b32_e32 v74, 16, v19
	v_and_b32_e32 v75, 0xffff0000, v19
	v_pk_add_f32 v[66:67], v[66:67], v[48:49] neg_lo:[0,1] neg_hi:[0,1]
	v_pk_fma_f32 v[66:67], v[66:67], v[68:69], v[48:49]
	v_pk_add_f32 v[48:49], v[74:75], v[48:49] neg_lo:[0,1] neg_hi:[0,1]
	v_lshlrev_b32_e32 v68, 16, v24
	v_pk_fma_f32 v[48:49], v[48:49], v[76:77], v[66:67]
	v_lshlrev_b32_e32 v66, 16, v16
	v_and_b32_e32 v67, 0xffff0000, v16
	v_and_b32_e32 v69, 0xffff0000, v24
	v_lshlrev_b32_e32 v74, 16, v20
	v_and_b32_e32 v75, 0xffff0000, v20
	v_pk_add_f32 v[68:69], v[68:69], v[66:67] neg_lo:[0,1] neg_hi:[0,1]
	v_pk_fma_f32 v[68:69], v[68:69], v[70:71], v[66:67]
	v_pk_add_f32 v[66:67], v[74:75], v[66:67] neg_lo:[0,1] neg_hi:[0,1]
	v_lshlrev_b32_e32 v70, 16, v25
	s_waitcnt lgkmcnt(0)
	v_pk_fma_f32 v[68:69], v[66:67], v[78:79], v[68:69]
	v_lshlrev_b32_e32 v66, 16, v17
	v_and_b32_e32 v67, 0xffff0000, v17
	v_and_b32_e32 v71, 0xffff0000, v25
	v_lshlrev_b32_e32 v74, 16, v21
	v_and_b32_e32 v75, 0xffff0000, v21
	v_pk_add_f32 v[70:71], v[70:71], v[66:67] neg_lo:[0,1] neg_hi:[0,1]
	v_cvt_pk_bf16_f32 v68, v68, v69
	v_pk_fma_f32 v[70:71], v[70:71], v[72:73], v[66:67]
	v_pk_add_f32 v[66:67], v[74:75], v[66:67] neg_lo:[0,1] neg_hi:[0,1]
	v_pk_fma_f32 v[70:71], v[66:67], v[80:81], v[70:71]
	v_cvt_pk_bf16_f32 v66, v26, v27
	v_cvt_pk_bf16_f32 v67, v48, v49
	v_cvt_pk_bf16_f32 v69, v70, v71
	ds_write_b128 v206, v[66:69] offset:43008

.LBB0_340:
	s_or_b64 exec, exec, s[24:25]
	s_and_b32 s35, s0, 1
	s_cmp_eq_u32 s51, 0
	s_cbranch_scc0 .Ltw_notfirst
	s_waitcnt vmcnt(0)
	v_lshl_add_u32 v47, s35, 9, v180
	ds_read_b128 v[66:69], v47
	ds_read_b128 v[70:73], v47 offset:16
	ds_read_b128 v[74:77], v47 offset:256
	ds_read_b128 v[78:81], v47 offset:272
	s_mov_b32 s30, 0x4038aa3b
	s_waitcnt lgkmcnt(1)
	v_lshlrev_b32_e32 v26, 16, v2
	v_and_b32_e32 v27, 0xffff0000, v2
	v_lshlrev_b32_e32 v48, 16, v10
	v_and_b32_e32 v49, 0xffff0000, v10
	v_lshlrev_b32_e32 v82, 16, v6
	v_and_b32_e32 v83, 0xffff0000, v6
	v_pk_add_f32 v[48:49], v[48:49], v[26:27] neg_lo:[0,1] neg_hi:[0,1]
	v_pk_add_f32 v[82:83], v[82:83], v[26:27] neg_lo:[0,1] neg_hi:[0,1]
	v_pk_fma_f32 v[48:49], v[48:49], v[66:67], v[26:27]
	v_pk_fma_f32 v[48:49], v[82:83], v[74:75], v[48:49]
	v_pk_mul_f32 v[66:67], v[48:49], s[30:31] op_sel_hi:[1,0]
	v_exp_f32_e32 v66, v66
	v_exp_f32_e32 v67, v67
	v_lshlrev_b32_e32 v26, 16, v3
	v_and_b32_e32 v27, 0xffff0000, v3
	v_lshlrev_b32_e32 v48, 16, v11
	v_and_b32_e32 v49, 0xffff0000, v11
	v_lshlrev_b32_e32 v82, 16, v7
	v_and_b32_e32 v83, 0xffff0000, v7
	v_pk_add_f32 v[48:49], v[48:49], v[26:27] neg_lo:[0,1] neg_hi:[0,1]
	v_pk_add_f32 v[82:83], v[82:83], v[26:27] neg_lo:[0,1] neg_hi:[0,1]
	v_pk_fma_f32 v[48:49], v[48:49], v[68:69], v[26:27]
	v_pk_fma_f32 v[48:49], v[82:83], v[76:77], v[48:49]
	v_pk_mul_f32 v[68:69], v[48:49], s[30:31] op_sel_hi:[1,0]
	v_pk_add_f32 v[66:67], v[66:67], 1.0 op_sel_hi:[1,0]
	v_rcp_f32_e32 v66, v66
	v_rcp_f32_e32 v67, v67
	v_exp_f32_e32 v68, v68
	v_exp_f32_e32 v69, v69
	s_waitcnt lgkmcnt(0)
	v_lshlrev_b32_e32 v26, 16, v4
	v_and_b32_e32 v27, 0xffff0000, v4
	v_lshlrev_b32_e32 v48, 16, v12
	v_and_b32_e32 v49, 0xffff0000, v12
	v_lshlrev_b32_e32 v82, 16, v8
	v_and_b32_e32 v83, 0xffff0000, v8
	v_pk_add_f32 v[48:49], v[48:49], v[26:27] neg_lo:[0,1] neg_hi:[0,1]
	v_pk_add_f32 v[82:83], v[82:83], v[26:27] neg_lo:[0,1] neg_hi:[0,1]
	v_pk_fma_f32 v[48:49], v[48:49], v[70:71], v[26:27]
	v_pk_fma_f32 v[48:49], v[82:83], v[78:79], v[48:49]
	v_pk_mul_f32 v[70:71], v[48:49], s[30:31] op_sel_hi:[1,0]
	v_pk_add_f32 v[68:69], v[68:69], 1.0 op_sel_hi:[1,0]
	v_rcp_f32_e32 v68, v68
	v_rcp_f32_e32 v69, v69
	v_exp_f32_e32 v70, v70
	v_exp_f32_e32 v71, v71
	v_lshlrev_b32_e32 v26, 16, v5
	v_and_b32_e32 v27, 0xffff0000, v5
	v_lshlrev_b32_e32 v48, 16, v13
	v_and_b32_e32 v49, 0xffff0000, v13
	v_lshlrev_b32_e32 v82, 16, v9
	v_and_b32_e32 v83, 0xffff0000, v9
	v_pk_add_f32 v[48:49], v[48:49], v[26:27] neg_lo:[0,1] neg_hi:[0,1]
	v_pk_add_f32 v[82:83], v[82:83], v[26:27] neg_lo:[0,1] neg_hi:[0,1]
	v_pk_fma_f32 v[48:49], v[48:49], v[72:73], v[26:27]
	v_pk_fma_f32 v[48:49], v[82:83], v[80:81], v[48:49]
	v_pk_mul_f32 v[72:73], v[48:49], s[30:31] op_sel_hi:[1,0]
	v_pk_add_f32 v[70:71], v[70:71], 1.0 op_sel_hi:[1,0]
	v_rcp_f32_e32 v70, v70
	v_rcp_f32_e32 v71, v71
	v_exp_f32_e32 v72, v72
	v_exp_f32_e32 v73, v73
	v_pk_fma_f32 v[66:67], v[66:67], 2.0, 1.0 op_sel_hi:[1,0,0] neg_lo:[1,0,0] neg_hi:[1,0,0]
	v_pk_fma_f32 v[68:69], v[68:69], 2.0, 1.0 op_sel_hi:[1,0,0] neg_lo:[1,0,0] neg_hi:[1,0,0]
	v_pk_add_f32 v[72:73], v[72:73], 1.0 op_sel_hi:[1,0]
	v_rcp_f32_e32 v72, v72
	v_rcp_f32_e32 v73, v73
	v_pk_fma_f32 v[70:71], v[70:71], 2.0, 1.0 op_sel_hi:[1,0,0] neg_lo:[1,0,0] neg_hi:[1,0,0]
	v_cvt_pk_bf16_f32 v74, v66, v67
	v_cvt_pk_bf16_f32 v75, v68, v69
	v_cvt_pk_bf16_f32 v76, v70, v71
	v_pk_fma_f32 v[72:73], v[72:73], 2.0, 1.0 op_sel_hi:[1,0,0] neg_lo:[1,0,0] neg_hi:[1,0,0]
	v_cvt_pk_bf16_f32 v77, v72, v73
	ds_write_b128 v206, v[74:77] offset:32768
	ds_read_b128 v[66:69], v47 offset:1024
	ds_read_b128 v[70:73], v47 offset:1040
	ds_read_b128 v[74:77], v47 offset:1280
	ds_read_b128 v[78:81], v47 offset:1296
	v_lshlrev_b32_e32 v26, 16, v14
	v_and_b32_e32 v27, 0xffff0000, v14
	v_lshlrev_b32_e32 v48, 16, v22
	v_and_b32_e32 v49, 0xffff0000, v22
	v_lshlrev_b32_e32 v82, 16, v18
	v_and_b32_e32 v83, 0xffff0000, v18
	v_pk_add_f32 v[48:49], v[48:49], v[26:27] neg_lo:[0,1] neg_hi:[0,1]
	s_waitcnt lgkmcnt(3)
	v_pk_fma_f32 v[48:49], v[48:49], v[66:67], v[26:27]
	v_pk_add_f32 v[26:27], v[82:83], v[26:27] neg_lo:[0,1] neg_hi:[0,1]
	v_lshlrev_b32_e32 v66, 16, v23
	s_waitcnt lgkmcnt(1)
	v_pk_fma_f32 v[26:27], v[26:27], v[74:75], v[48:49]
	v_lshlrev_b32_e32 v48, 16, v15
	v_and_b32_e32 v49, 0xffff0000, v15
	v_and_b32_e32 v67, 0xffff0000, v23
	v_lshlrev_b32_e32 v74, 16, v19
	v_and_b32_e32 v75, 0xffff0000, v19
	v_pk_add_f32 v[66:67], v[66:67], v[48:49] neg_lo:[0,1] neg_hi:[0,1]
	v_pk_fma_f32 v[66:67], v[66:67], v[68:69], v[48:49]
	v_pk_add_f32 v[48:49], v[74:75], v[48:49] neg_lo:[0,1] neg_hi:[0,1]
	v_lshlrev_b32_e32 v68, 16, v24
	v_pk_fma_f32 v[48:49], v[48:49], v[76:77], v[66:67]
	v_lshlrev_b32_e32 v66, 16, v16
	v_and_b32_e32 v67, 0xffff0000, v16
	v_and_b32_e32 v69, 0xffff0000, v24
	v_lshlrev_b32_e32 v74, 16, v20
	v_and_b32_e32 v75, 0xffff0000, v20
	v_pk_add_f32 v[68:69], v[68:69], v[66:67] neg_lo:[0,1] neg_hi:[0,1]
	v_pk_fma_f32 v[68:69], v[68:69], v[70:71], v[66:67]
	v_pk_add_f32 v[66:67], v[74:75], v[66:67] neg_lo:[0,1] neg_hi:[0,1]
	v_lshlrev_b32_e32 v70, 16, v25
	s_waitcnt lgkmcnt(0)
	v_pk_fma_f32 v[68:69], v[66:67], v[78:79], v[68:69]
	v_lshlrev_b32_e32 v66, 16, v17
	v_and_b32_e32 v67, 0xffff0000, v17
	v_and_b32_e32 v71, 0xffff0000, v25
	v_lshlrev_b32_e32 v74, 16, v21
	v_and_b32_e32 v75, 0xffff0000, v21
	v_pk_add_f32 v[70:71], v[70:71], v[66:67] neg_lo:[0,1] neg_hi:[0,1]
	v_cvt_pk_bf16_f32 v68, v68, v69
	v_pk_fma_f32 v[70:71], v[70:71], v[72:73], v[66:67]
	v_pk_add_f32 v[66:67], v[74:75], v[66:67] neg_lo:[0,1] neg_hi:[0,1]
	v_pk_fma_f32 v[70:71], v[66:67], v[80:81], v[70:71]
	v_cvt_pk_bf16_f32 v66, v26, v27
	v_cvt_pk_bf16_f32 v67, v48, v49
	v_cvt_pk_bf16_f32 v69, v70, v71
	ds_write_b128 v206, v[66:69] offset:43008

.LBB0_342:
	s_or_b64 exec, exec, s[24:25]
	v_lshlrev_b32_e32 v28, 2, v47
	s_movk_i32 s25, 0xff60
	s_and_b64 vcc, s[54:55], exec
	s_cselect_b32 s24, s25, 0xa0
	v_cndmask_b32_e64 v70, v169, v170, s[54:55]
	v_add_u32_e32 v71, s24, v70
	v_add_u32_e32 v72, s24, v71
	v_add_u32_e32 v73, s24, v72
	v_add_u32_e32 v74, s24, v73
	v_add_u32_e32 v75, s24, v74
	ds_read_b32 v150, v70 offset:42848
	ds_read_b32 v151, v71 offset:42848
	ds_read_b32 v141, v72 offset:42848
	ds_read_b32 v240, v73 offset:42848
	ds_read_b32 v238, v74 offset:42848
	ds_read_b32 v236, v75 offset:42848
	ds_read_b32 v140, v70 offset:53408
	ds_read_b32 v154, v71 offset:53408
	ds_read_b32 v155, v72 offset:53408
	ds_read_b32 v239, v73 offset:53408
	ds_read_b32 v237, v74 offset:53408
	ds_read_b32 v235, v75 offset:53408
	ds_read_b32 v137, v70 offset:63968
	ds_read_b32 v229, v71 offset:63968
	ds_read_b32 v230, v72 offset:63968
	ds_read_b32 v232, v73 offset:63968
	ds_read_b32 v233, v74 offset:63968
	ds_read_b32 v231, v75 offset:63968
	v_lshl_add_u32 v67, v66, 2, 0
	s_waitcnt lgkmcnt(0)
	s_barrier
	v_add_u32_e32 v67, 0x8000, v67
	ds_read2_b64 v[90:93], v67 offset1:32
	ds_read2_b64 v[86:89], v67 offset0:64 offset1:96
	ds_read2_b64 v[82:85], v67 offset0:128 offset1:160
	ds_read2_b64 v[78:81], v67 offset0:192 offset1:224
	v_cmp_eq_u32_e32 vcc, 15, v135
	s_and_saveexec_b64 s[24:25], vcc
	s_cbranch_execz .LBB0_344
	s_waitcnt lgkmcnt(3)
	v_pk_add_f32 v[68:69], v[90:91], 0 op_sel_hi:[1,0]
	v_mov_b32_e32 v67, v66
	v_pk_add_f32 v[68:69], v[68:69], v[92:93]
	s_waitcnt lgkmcnt(2)
	v_pk_add_f32 v[68:69], v[68:69], v[86:87]
	v_lshl_add_u32 v67, v67, 2, 0
	v_pk_add_f32 v[68:69], v[68:69], v[88:89]
	v_add_u32_e32 v67, 0x22c00, v67
	s_waitcnt lgkmcnt(1)
	v_pk_add_f32 v[68:69], v[68:69], v[82:83]
	s_nop 0
	v_pk_add_f32 v[68:69], v[68:69], v[84:85]
	s_waitcnt lgkmcnt(0)
	v_pk_add_f32 v[68:69], v[68:69], v[78:79]
	s_nop 0
	v_pk_add_f32 v[68:69], v[68:69], v[80:81]
	s_nop 0
	v_exp_f32_e32 v68, v68
	v_exp_f32_e32 v69, v69
	ds_write_b64 v67, v[68:69]

.LBB0_652:
	s_or_b64 exec, exec, s[2:3]
	v_lshlrev_b64 v[214:215], 2, v[210:211]
	s_waitcnt lgkmcnt(0)
	s_barrier
	v_lshl_add_u64 v[0:1], s[94:95], 0, v[214:215]
	global_load_dwordx4 v[206:209], v[0:1], off
	global_load_dwordx4 v[202:205], v[0:1], off offset:64
	global_load_dwordx4 v[198:201], v[0:1], off offset:512
	global_load_dwordx4 v[194:197], v[0:1], off offset:576
	v_lshl_add_u32 v1, v216, 2, 0
	v_add_u32_e32 v217, 0x2000, v1
	ds_read2_b32 v[222:223], v217 offset1:16
	v_add_u32_e32 v0, s18, v216
	v_ashrrev_i32_e32 v1, 31, v0
	v_add_u32_e32 v220, 16, v0
	v_lshlrev_b64 v[224:225], 12, v[0:1]
	s_waitcnt lgkmcnt(0)
	v_pk_mul_f32 v[128:129], v[128:129], v[222:223] op_sel_hi:[1,0]
	v_pk_mul_f32 v[126:127], v[126:127], v[222:223] op_sel_hi:[1,0]
	v_pk_mul_f32 v[124:125], v[124:125], v[222:223] op_sel_hi:[1,0]
	v_pk_mul_f32 v[122:123], v[122:123], v[222:223] op_sel_hi:[1,0]
	v_pk_mul_f32 v[112:113], v[112:113], v[222:223] op_sel_hi:[1,0]
	v_pk_mul_f32 v[110:111], v[110:111], v[222:223] op_sel_hi:[1,0]
	v_pk_mul_f32 v[108:109], v[108:109], v[222:223] op_sel_hi:[1,0]
	v_pk_mul_f32 v[106:107], v[106:107], v[222:223] op_sel_hi:[1,0]
	v_mov_b32_e32 v222, v223
	v_ashrrev_i32_e32 v221, 31, v220
	v_pk_mul_f32 v[116:117], v[116:117], v[222:223] op_sel_hi:[1,0]
	v_mov_b32_e32 v216, 0x7fc00000
	v_lshl_add_u64 v[224:225], s[96:97], 0, v[224:225]
	v_lshlrev_b64 v[220:221], 12, v[220:221]
	v_pk_mul_f32 v[120:121], v[120:121], v[222:223] op_sel_hi:[1,0]
	v_pk_mul_f32 v[118:119], v[118:119], v[222:223] op_sel_hi:[1,0]
	v_pk_mul_f32 v[114:115], v[114:115], v[222:223] op_sel_hi:[1,0]
	v_pk_mul_f32 v[104:105], v[104:105], v[222:223] op_sel_hi:[1,0]
	v_pk_mul_f32 v[102:103], v[102:103], v[222:223] op_sel_hi:[1,0]
	v_cmp_eq_u32_e32 vcc, 0, v218
	v_pk_mul_f32 v[96:97], v[96:97], v[222:223] op_sel_hi:[1,0]
	v_pk_mul_f32 v[94:95], v[94:95], v[222:223] op_sel_hi:[1,0]
	v_lshl_add_u64 v[224:225], v[224:225], 0, v[214:215]
	v_lshl_add_u64 v[220:221], s[96:97], 0, v[220:221]
	v_lshl_add_u64 v[220:221], v[220:221], 0, v[214:215]
	s_waitcnt vmcnt(0)
	v_pk_fma_f32 v[126:127], v[206:207], v[126:127], v[182:183]
	v_pk_fma_f32 v[128:129], v[208:209], v[128:129], v[184:185]
	v_pk_fma_f32 v[124:125], v[204:205], v[124:125], v[180:181]
	v_pk_fma_f32 v[112:113], v[200:201], v[112:113], v[172:173]
	v_pk_fma_f32 v[172:173], v[204:205], v[116:117], v[188:189]
	v_pk_fma_f32 v[122:123], v[202:203], v[122:123], v[178:179]
	v_pk_fma_f32 v[110:111], v[198:199], v[110:111], v[170:171]
	v_pk_fma_f32 v[166:167], v[194:195], v[106:107], v[166:167]
	v_pk_fma_f32 v[168:169], v[196:197], v[108:109], v[168:169]
	v_pk_fma_f32 v[118:119], v[206:207], v[118:119], v[190:191]
	v_pk_fma_f32 v[120:121], v[208:209], v[120:121], v[192:193]
	v_pk_fma_f32 v[170:171], v[202:203], v[114:115], v[186:187]
	v_pk_fma_f32 v[174:175], v[198:199], v[102:103], v[174:175]
	v_pk_fma_f32 v[176:177], v[200:201], v[104:105], v[176:177]
	v_cndmask_b32_e32 v105, v216, v129, vcc
	v_cndmask_b32_e32 v104, v216, v128, vcc
	v_cndmask_b32_e32 v103, v216, v127, vcc
	v_cndmask_b32_e32 v102, v216, v126, vcc
	v_cndmask_b32_e32 v109, v216, v125, vcc
	v_cndmask_b32_e32 v108, v216, v124, vcc
	v_cndmask_b32_e32 v125, v216, v173, vcc
	v_cndmask_b32_e32 v124, v216, v172, vcc
	v_pk_fma_f32 v[94:95], v[194:195], v[94:95], v[162:163]
	v_pk_fma_f32 v[96:97], v[196:197], v[96:97], v[164:165]
	v_cndmask_b32_e32 v107, v216, v123, vcc
	v_cndmask_b32_e32 v106, v216, v122, vcc
	v_cndmask_b32_e32 v113, v216, v113, vcc
	v_cndmask_b32_e32 v112, v216, v112, vcc
	v_cndmask_b32_e32 v111, v216, v111, vcc
	v_cndmask_b32_e32 v110, v216, v110, vcc
	v_cndmask_b32_e32 v117, v216, v169, vcc
	v_cndmask_b32_e32 v116, v216, v168, vcc
	v_cndmask_b32_e32 v115, v216, v167, vcc
	v_cndmask_b32_e32 v114, v216, v166, vcc
	v_cndmask_b32_e32 v121, v216, v121, vcc
	v_cndmask_b32_e32 v120, v216, v120, vcc
	v_cndmask_b32_e32 v119, v216, v119, vcc
	v_cndmask_b32_e32 v118, v216, v118, vcc
	v_cndmask_b32_e32 v123, v216, v171, vcc
	v_cndmask_b32_e32 v122, v216, v170, vcc
	v_cndmask_b32_e32 v127, v216, v177, vcc
	v_cndmask_b32_e32 v126, v216, v176, vcc
	global_store_dwordx4 v[224:225], v[102:105], off
	global_store_dwordx4 v[224:225], v[106:109], off offset:64
	global_store_dwordx4 v[224:225], v[110:113], off offset:512
	global_store_dwordx4 v[224:225], v[114:117], off offset:576
	global_store_dwordx4 v[220:221], v[118:121], off
	global_store_dwordx4 v[220:221], v[122:125], off offset:64
	v_cndmask_b32_e32 v97, v216, v97, vcc
	v_cndmask_b32_e32 v96, v216, v96, vcc
	v_cndmask_b32_e32 v125, v216, v175, vcc
	v_cndmask_b32_e32 v124, v216, v174, vcc
	v_cndmask_b32_e32 v95, v216, v95, vcc
	v_cndmask_b32_e32 v94, v216, v94, vcc
	global_store_dwordx4 v[220:221], v[124:127], off offset:512
	global_store_dwordx4 v[220:221], v[94:97], off offset:576
	v_add_u32_e32 v222, 0x80, v0
	v_lshlrev_b32_e32 v222, 12, v222
	v_mov_b32_e32 v223, 0
	v_lshl_add_u64 v[224:225], v[212:213], 0, v[222:223]
	global_load_dwordx4 v[162:165], v[224:225], off
	global_load_dwordx4 v[166:169], v[224:225], off offset:64
	global_load_dwordx4 v[170:173], v[224:225], off offset:512
	global_load_dwordx4 v[174:177], v[224:225], off offset:576
	v_add_u32_e32 v222, 0x10000, v222
	v_lshl_add_u64 v[224:225], v[212:213], 0, v[222:223]
	global_load_dwordx4 v[178:181], v[224:225], off
	global_load_dwordx4 v[182:185], v[224:225], off offset:64
	global_load_dwordx4 v[186:189], v[224:225], off offset:512
	global_load_dwordx4 v[190:193], v[224:225], off offset:576
	ds_read2_b32 v[102:103], v217 offset0:32 offset1:48
	v_add_u32_e32 v104, 32, v0
	v_ashrrev_i32_e32 v105, 31, v104
	s_waitcnt lgkmcnt(0)
	v_pk_mul_f32 v[94:95], v[100:101], v[102:103] op_sel_hi:[1,0]
	v_pk_mul_f32 v[96:97], v[98:99], v[102:103] op_sel_hi:[1,0]
	v_pk_fma_f32 v[94:95], v[208:209], v[94:95], v[160:161]
	v_pk_fma_f32 v[98:99], v[206:207], v[96:97], v[158:159]
	v_cndmask_b32_e32 v97, v216, v95, vcc
	v_cndmask_b32_e32 v96, v216, v94, vcc
	v_cndmask_b32_e32 v95, v216, v99, vcc
	v_cndmask_b32_e32 v94, v216, v98, vcc
	v_lshlrev_b64 v[98:99], 12, v[104:105]
	v_pk_mul_f32 v[88:89], v[88:89], v[102:103] op_sel_hi:[1,0]
	v_pk_mul_f32 v[86:87], v[86:87], v[102:103] op_sel_hi:[1,0]
	v_lshl_add_u64 v[98:99], s[96:97], 0, v[98:99]
	v_pk_fma_f32 v[86:87], v[198:199], v[86:87], v[150:151]
	v_pk_fma_f32 v[88:89], v[200:201], v[88:89], v[152:153]
	v_pk_mul_f32 v[80:81], v[80:81], v[102:103] op_sel_hi:[1,0]
	v_pk_mul_f32 v[78:79], v[78:79], v[102:103] op_sel_hi:[1,0]
	v_lshl_add_u64 v[98:99], v[98:99], 0, v[214:215]
	v_cndmask_b32_e32 v89, v216, v89, vcc
	v_cndmask_b32_e32 v88, v216, v88, vcc
	v_cndmask_b32_e32 v87, v216, v87, vcc
	v_cndmask_b32_e32 v86, v216, v86, vcc
	v_pk_fma_f32 v[78:79], v[194:195], v[78:79], v[146:147]
	v_pk_fma_f32 v[80:81], v[196:197], v[80:81], v[148:149]
	global_store_dwordx4 v[98:99], v[86:89], off offset:512
	v_cndmask_b32_e32 v81, v216, v81, vcc
	v_cndmask_b32_e32 v80, v216, v80, vcc
	v_cndmask_b32_e32 v79, v216, v79, vcc
	v_cndmask_b32_e32 v78, v216, v78, vcc
	v_mov_b32_e32 v88, v103
	global_store_dwordx4 v[98:99], v[78:81], off offset:576
	v_add_u32_e32 v86, 48, v0
	v_ashrrev_i32_e32 v87, 31, v86
	v_pk_mul_f32 v[78:79], v[84:85], v[88:89] op_sel_hi:[1,0]
	v_pk_mul_f32 v[80:81], v[82:83], v[88:89] op_sel_hi:[1,0]
	v_pk_fma_f32 v[78:79], v[208:209], v[78:79], v[144:145]
	v_pk_fma_f32 v[82:83], v[206:207], v[80:81], v[142:143]
	v_cndmask_b32_e32 v81, v216, v79, vcc
	v_cndmask_b32_e32 v80, v216, v78, vcc
	v_cndmask_b32_e32 v79, v216, v83, vcc
	v_cndmask_b32_e32 v78, v216, v82, vcc
	v_lshlrev_b64 v[82:83], 12, v[86:87]
	v_pk_mul_f32 v[72:73], v[72:73], v[88:89] op_sel_hi:[1,0]
	v_pk_mul_f32 v[70:71], v[70:71], v[88:89] op_sel_hi:[1,0]
	v_lshl_add_u64 v[82:83], s[96:97], 0, v[82:83]
	v_pk_fma_f32 v[70:71], v[198:199], v[70:71], v[134:135]
	v_pk_fma_f32 v[72:73], v[200:201], v[72:73], v[136:137]
	v_pk_mul_f32 v[92:93], v[92:93], v[102:103] op_sel_hi:[1,0]
	v_pk_mul_f32 v[90:91], v[90:91], v[102:103] op_sel_hi:[1,0]
	v_lshl_add_u64 v[82:83], v[82:83], 0, v[214:215]
	v_pk_mul_f32 v[76:77], v[76:77], v[88:89] op_sel_hi:[1,0]
	v_pk_mul_f32 v[74:75], v[74:75], v[88:89] op_sel_hi:[1,0]
	v_cndmask_b32_e32 v73, v216, v73, vcc
	v_cndmask_b32_e32 v72, v216, v72, vcc
	v_cndmask_b32_e32 v71, v216, v71, vcc
	v_cndmask_b32_e32 v70, v216, v70, vcc
	v_pk_mul_f32 v[68:69], v[68:69], v[88:89] op_sel_hi:[1,0]
	v_pk_mul_f32 v[66:67], v[66:67], v[88:89] op_sel_hi:[1,0]
	v_pk_fma_f32 v[90:91], v[202:203], v[90:91], v[154:155]
	v_pk_fma_f32 v[92:93], v[204:205], v[92:93], v[156:157]
	v_pk_fma_f32 v[74:75], v[202:203], v[74:75], v[138:139]
	v_pk_fma_f32 v[76:77], v[204:205], v[76:77], v[140:141]
	global_store_dwordx4 v[82:83], v[70:73], off offset:512
	v_pk_fma_f32 v[66:67], v[194:195], v[66:67], v[130:131]
	v_pk_fma_f32 v[68:69], v[196:197], v[68:69], v[132:133]
	v_add_u32_e32 v70, 0x80, v0
	v_cndmask_b32_e32 v93, v216, v93, vcc
	v_cndmask_b32_e32 v92, v216, v92, vcc
	v_cndmask_b32_e32 v91, v216, v91, vcc
	v_cndmask_b32_e32 v90, v216, v90, vcc
	v_cndmask_b32_e32 v77, v216, v77, vcc
	v_cndmask_b32_e32 v76, v216, v76, vcc
	v_cndmask_b32_e32 v75, v216, v75, vcc
	v_cndmask_b32_e32 v74, v216, v74, vcc
	v_cndmask_b32_e32 v69, v216, v69, vcc
	v_cndmask_b32_e32 v68, v216, v68, vcc
	v_cndmask_b32_e32 v67, v216, v67, vcc
	v_cndmask_b32_e32 v66, v216, v66, vcc
	v_ashrrev_i32_e32 v71, 31, v70
	global_store_dwordx4 v[98:99], v[94:97], off
	global_store_dwordx4 v[98:99], v[90:93], off offset:64
	global_store_dwordx4 v[82:83], v[78:81], off
	global_store_dwordx4 v[82:83], v[74:77], off offset:64
	global_store_dwordx4 v[82:83], v[66:69], off offset:576
	v_add_u32_e32 v222, 0x10000, v222
	v_lshl_add_u64 v[224:225], v[212:213], 0, v[222:223]
	global_load_dwordx4 v[130:133], v[224:225], off
	global_load_dwordx4 v[134:137], v[224:225], off offset:64
	global_load_dwordx4 v[138:141], v[224:225], off offset:512
	global_load_dwordx4 v[142:145], v[224:225], off offset:576
	v_add_u32_e32 v222, 0x10000, v222
	v_lshl_add_u64 v[224:225], v[212:213], 0, v[222:223]
	global_load_dwordx4 v[146:149], v[224:225], off
	global_load_dwordx4 v[150:153], v[224:225], off offset:64
	global_load_dwordx4 v[154:157], v[224:225], off offset:512
	global_load_dwordx4 v[158:161], v[224:225], off offset:576
	ds_read2_b32 v[74:75], v217 offset0:128 offset1:144
	ds_read2_b32 v[76:77], v217 offset0:160 offset1:176
	v_lshl_add_u64 v[82:83], s[96:97], 0, v[214:215]
	v_add_u32_e32 v222, 0xfffd0000, v222
	s_waitcnt lgkmcnt(0)
	v_mov_b32_e32 v78, v75
	v_mov_b32_e32 v80, v77
	v_pk_mul_f32 v[62:63], v[62:63], v[74:75] op_sel_hi:[1,0]
	v_pk_mul_f32 v[64:65], v[64:65], v[74:75] op_sel_hi:[1,0]
	v_pk_mul_f32 v[58:59], v[58:59], v[74:75] op_sel_hi:[1,0]
	v_pk_mul_f32 v[60:61], v[60:61], v[74:75] op_sel_hi:[1,0]
	v_pk_mul_f32 v[54:55], v[54:55], v[74:75] op_sel_hi:[1,0]
	v_pk_mul_f32 v[56:57], v[56:57], v[74:75] op_sel_hi:[1,0]
	v_pk_mul_f32 v[46:47], v[46:47], v[74:75] op_sel_hi:[1,0]
	v_pk_mul_f32 v[48:49], v[48:49], v[74:75] op_sel_hi:[1,0]
	v_lshl_add_u64 v[84:85], v[82:83], 0, v[222:223]
	s_waitcnt vmcnt(20)
	v_pk_fma_f32 v[62:63], v[206:207], v[62:63], v[162:163]
	v_pk_fma_f32 v[64:65], v[208:209], v[64:65], v[164:165]
	v_pk_fma_f32 v[58:59], v[202:203], v[58:59], v[166:167]
	v_pk_fma_f32 v[60:61], v[204:205], v[60:61], v[168:169]
	v_pk_fma_f32 v[54:55], v[198:199], v[54:55], v[170:171]
	v_pk_fma_f32 v[56:57], v[200:201], v[56:57], v[172:173]
	v_pk_fma_f32 v[46:47], v[194:195], v[46:47], v[174:175]
	v_pk_fma_f32 v[48:49], v[196:197], v[48:49], v[176:177]
	v_cndmask_b32_e32 v62, v216, v62, vcc
	v_cndmask_b32_e32 v63, v216, v63, vcc
	v_cndmask_b32_e32 v64, v216, v64, vcc
	v_cndmask_b32_e32 v65, v216, v65, vcc
	v_cndmask_b32_e32 v58, v216, v58, vcc
	v_cndmask_b32_e32 v59, v216, v59, vcc
	v_cndmask_b32_e32 v60, v216, v60, vcc
	v_cndmask_b32_e32 v61, v216, v61, vcc
	v_cndmask_b32_e32 v54, v216, v54, vcc
	v_cndmask_b32_e32 v55, v216, v55, vcc
	v_cndmask_b32_e32 v56, v216, v56, vcc
	v_cndmask_b32_e32 v57, v216, v57, vcc
	v_cndmask_b32_e32 v46, v216, v46, vcc
	v_cndmask_b32_e32 v47, v216, v47, vcc
	v_cndmask_b32_e32 v48, v216, v48, vcc
	v_cndmask_b32_e32 v49, v216, v49, vcc
	global_store_dwordx4 v[84:85], v[62:65], off
	global_store_dwordx4 v[84:85], v[58:61], off offset:64
	global_store_dwordx4 v[84:85], v[54:57], off offset:512
	global_store_dwordx4 v[84:85], v[46:49], off offset:576
	v_pk_mul_f32 v[50:51], v[50:51], v[78:79] op_sel_hi:[1,0]
	v_pk_mul_f32 v[52:53], v[52:53], v[78:79] op_sel_hi:[1,0]
	v_pk_mul_f32 v[42:43], v[42:43], v[78:79] op_sel_hi:[1,0]
	v_pk_mul_f32 v[44:45], v[44:45], v[78:79] op_sel_hi:[1,0]
	v_pk_mul_f32 v[38:39], v[38:39], v[78:79] op_sel_hi:[1,0]
	v_pk_mul_f32 v[40:41], v[40:41], v[78:79] op_sel_hi:[1,0]
	v_pk_mul_f32 v[30:31], v[30:31], v[78:79] op_sel_hi:[1,0]
	v_pk_mul_f32 v[32:33], v[32:33], v[78:79] op_sel_hi:[1,0]
	v_add_u32_e32 v222, 0x10000, v222
	v_lshl_add_u64 v[84:85], v[82:83], 0, v[222:223]
	s_waitcnt vmcnt(20)
	v_pk_fma_f32 v[50:51], v[206:207], v[50:51], v[178:179]
	v_pk_fma_f32 v[52:53], v[208:209], v[52:53], v[180:181]
	v_pk_fma_f32 v[42:43], v[202:203], v[42:43], v[182:183]
	v_pk_fma_f32 v[44:45], v[204:205], v[44:45], v[184:185]
	v_pk_fma_f32 v[38:39], v[198:199], v[38:39], v[186:187]
	v_pk_fma_f32 v[40:41], v[200:201], v[40:41], v[188:189]
	v_pk_fma_f32 v[30:31], v[194:195], v[30:31], v[190:191]
	v_pk_fma_f32 v[32:33], v[196:197], v[32:33], v[192:193]
	v_cndmask_b32_e32 v50, v216, v50, vcc
	v_cndmask_b32_e32 v51, v216, v51, vcc
	v_cndmask_b32_e32 v52, v216, v52, vcc
	v_cndmask_b32_e32 v53, v216, v53, vcc
	v_cndmask_b32_e32 v42, v216, v42, vcc
	v_cndmask_b32_e32 v43, v216, v43, vcc
	v_cndmask_b32_e32 v44, v216, v44, vcc
	v_cndmask_b32_e32 v45, v216, v45, vcc
	v_cndmask_b32_e32 v38, v216, v38, vcc
	v_cndmask_b32_e32 v39, v216, v39, vcc
	v_cndmask_b32_e32 v40, v216, v40, vcc
	v_cndmask_b32_e32 v41, v216, v41, vcc
	v_cndmask_b32_e32 v30, v216, v30, vcc
	v_cndmask_b32_e32 v31, v216, v31, vcc
	v_cndmask_b32_e32 v32, v216, v32, vcc
	v_cndmask_b32_e32 v33, v216, v33, vcc
	global_store_dwordx4 v[84:85], v[50:53], off
	global_store_dwordx4 v[84:85], v[42:45], off offset:64
	global_store_dwordx4 v[84:85], v[38:41], off offset:512
	global_store_dwordx4 v[84:85], v[30:33], off offset:576
	v_pk_mul_f32 v[34:35], v[34:35], v[76:77] op_sel_hi:[1,0]
	v_pk_mul_f32 v[36:37], v[36:37], v[76:77] op_sel_hi:[1,0]
	v_pk_mul_f32 v[26:27], v[26:27], v[76:77] op_sel_hi:[1,0]
	v_pk_mul_f32 v[28:29], v[28:29], v[76:77] op_sel_hi:[1,0]
	v_pk_mul_f32 v[22:23], v[22:23], v[76:77] op_sel_hi:[1,0]
	v_pk_mul_f32 v[24:25], v[24:25], v[76:77] op_sel_hi:[1,0]
	v_pk_mul_f32 v[14:15], v[14:15], v[76:77] op_sel_hi:[1,0]
	v_pk_mul_f32 v[16:17], v[16:17], v[76:77] op_sel_hi:[1,0]
	v_add_u32_e32 v222, 0x10000, v222
	v_lshl_add_u64 v[84:85], v[82:83], 0, v[222:223]
	s_waitcnt vmcnt(12)
	v_pk_fma_f32 v[34:35], v[206:207], v[34:35], v[130:131]
	v_pk_fma_f32 v[36:37], v[208:209], v[36:37], v[132:133]
	v_pk_fma_f32 v[26:27], v[202:203], v[26:27], v[134:135]
	v_pk_fma_f32 v[28:29], v[204:205], v[28:29], v[136:137]
	v_pk_fma_f32 v[22:23], v[198:199], v[22:23], v[138:139]
	v_pk_fma_f32 v[24:25], v[200:201], v[24:25], v[140:141]
	v_pk_fma_f32 v[14:15], v[194:195], v[14:15], v[142:143]
	v_pk_fma_f32 v[16:17], v[196:197], v[16:17], v[144:145]
	v_cndmask_b32_e32 v34, v216, v34, vcc
	v_cndmask_b32_e32 v35, v216, v35, vcc
	v_cndmask_b32_e32 v36, v216, v36, vcc
	v_cndmask_b32_e32 v37, v216, v37, vcc
	v_cndmask_b32_e32 v26, v216, v26, vcc
	v_cndmask_b32_e32 v27, v216, v27, vcc
	v_cndmask_b32_e32 v28, v216, v28, vcc
	v_cndmask_b32_e32 v29, v216, v29, vcc
	v_cndmask_b32_e32 v22, v216, v22, vcc
	v_cndmask_b32_e32 v23, v216, v23, vcc
	v_cndmask_b32_e32 v24, v216, v24, vcc
	v_cndmask_b32_e32 v25, v216, v25, vcc
	v_cndmask_b32_e32 v14, v216, v14, vcc
	v_cndmask_b32_e32 v15, v216, v15, vcc
	v_cndmask_b32_e32 v16, v216, v16, vcc
	v_cndmask_b32_e32 v17, v216, v17, vcc
	global_store_dwordx4 v[84:85], v[34:37], off
	global_store_dwordx4 v[84:85], v[26:29], off offset:64
	global_store_dwordx4 v[84:85], v[22:25], off offset:512
	global_store_dwordx4 v[84:85], v[14:17], off offset:576
	v_pk_mul_f32 v[18:19], v[18:19], v[80:81] op_sel_hi:[1,0]
	v_pk_mul_f32 v[20:21], v[20:21], v[80:81] op_sel_hi:[1,0]
	v_pk_mul_f32 v[10:11], v[10:11], v[80:81] op_sel_hi:[1,0]
	v_pk_mul_f32 v[12:13], v[12:13], v[80:81] op_sel_hi:[1,0]
	v_pk_mul_f32 v[6:7], v[6:7], v[80:81] op_sel_hi:[1,0]
	v_pk_mul_f32 v[8:9], v[8:9], v[80:81] op_sel_hi:[1,0]
	v_pk_mul_f32 v[2:3], v[2:3], v[80:81] op_sel_hi:[1,0]
	v_pk_mul_f32 v[4:5], v[4:5], v[80:81] op_sel_hi:[1,0]
	v_add_u32_e32 v222, 0x10000, v222
	v_lshl_add_u64 v[84:85], v[82:83], 0, v[222:223]
	s_waitcnt vmcnt(12)
	v_pk_fma_f32 v[18:19], v[206:207], v[18:19], v[146:147]
	v_pk_fma_f32 v[20:21], v[208:209], v[20:21], v[148:149]
	v_pk_fma_f32 v[10:11], v[202:203], v[10:11], v[150:151]
	v_pk_fma_f32 v[12:13], v[204:205], v[12:13], v[152:153]
	v_pk_fma_f32 v[6:7], v[198:199], v[6:7], v[154:155]
	v_pk_fma_f32 v[8:9], v[200:201], v[8:9], v[156:157]
	v_pk_fma_f32 v[2:3], v[194:195], v[2:3], v[158:159]
	v_pk_fma_f32 v[4:5], v[196:197], v[4:5], v[160:161]
	v_cndmask_b32_e32 v18, v216, v18, vcc
	v_cndmask_b32_e32 v19, v216, v19, vcc
	v_cndmask_b32_e32 v20, v216, v20, vcc
	v_cndmask_b32_e32 v21, v216, v21, vcc
	v_cndmask_b32_e32 v10, v216, v10, vcc
	v_cndmask_b32_e32 v11, v216, v11, vcc
	v_cndmask_b32_e32 v12, v216, v12, vcc
	v_cndmask_b32_e32 v13, v216, v13, vcc
	v_cndmask_b32_e32 v6, v216, v6, vcc
	v_cndmask_b32_e32 v7, v216, v7, vcc
	v_cndmask_b32_e32 v8, v216, v8, vcc
	v_cndmask_b32_e32 v9, v216, v9, vcc
	v_cndmask_b32_e32 v2, v216, v2, vcc
	v_cndmask_b32_e32 v3, v216, v3, vcc
	v_cndmask_b32_e32 v4, v216, v4, vcc
	v_cndmask_b32_e32 v5, v216, v5, vcc
	global_store_dwordx4 v[84:85], v[18:21], off
	global_store_dwordx4 v[84:85], v[10:13], off offset:64
	global_store_dwordx4 v[84:85], v[6:9], off offset:512
	global_store_dwordx4 v[84:85], v[2:5], off offset:576
